# v10 plus the next-tile-load reorder in the DSA loop (K/V and mask-word loads after the first K-fragment LDS reads)
# speedup vs baseline: 1.0062x; 1.0003x over previous
; #define LAS __attribute__((address_space(3)))
; __device__ __forceinline__ void mask_bits(f32x16& p0, f32x16& p1, unsigned lo, unsigned hi_w, int hi) {
;     const unsigned a = lo >> (4 * hi), b = hi_w >> (4 * hi); const unsigned NEGB = 0xFF800000u;
; #pragma unroll
;     for (int r = 0; r < 16; ++r) { const int c = (r & 3) + 8 * (r >> 2);
;         const unsigned ma = (unsigned)__builtin_amdgcn_sbfe((int)a, c, 1), mb = (unsigned)__builtin_amdgcn_sbfe((int)b, c, 1);
;         const float x0 = p0[r], x1 = p1[r];
;         p0[r] = __uint_as_float((__float_as_uint(x0) & ma) | (NEGB & ~ma));
;         p1[r] = __uint_as_float((__float_as_uint(x1) & mb) | (NEGB & ~mb)); }
; }
; __device__ __forceinline__ float max3f(float a, float b, float c) { return __builtin_fmaxf(__builtin_fmaxf(a, b), c); }
; __device__ __forceinline__ void partialSM(f32x16& p0, f32x16& p1, float& m_reg, float& mn, float& alpha, const float sc, const float C2) {
;     float pmax = max3f(p0[0], p0[1], p0[2]);
; #pragma unroll
;     for (int r = 3; r < 15; r += 2) pmax = max3f(pmax, p0[r], p0[r + 1]);
;     pmax = max3f(pmax, p0[15], p1[0]);
; #pragma unroll
;     for (int r = 1; r < 15; r += 2) pmax = max3f(pmax, p1[r], p1[r + 1]);
;     pmax = fmaxf(pmax, p1[15]);
;     { auto rr = __builtin_amdgcn_permlane32_swap(__float_as_uint(pmax), __float_as_uint(pmax), false, false);
;       pmax = fmaxf(__uint_as_float(rr[0]), __uint_as_float(rr[1])); }
; template <bool MLA>
; __device__ __forceinline__ void qkt2(f32x16& p0, f32x16& p1, const LAS char* lds, int kboff, int kroff, int r32, int hi, const half8* qr) {
;     const LAS char* kb[4];
; #pragma unroll
;     for (int dd = 0; dd < 4; ++dd) kb[dd] = lds + OFF_K + kboff + FA_KSWZ(r32, (dd * 16 + hi * 8) * 2);
;     constexpr int NG = MLA ? 6 : 4;
;     half8 fa0[2], fa1[2], fb0[2], fb1[2];
;     ...
; #pragma unroll
;     for (int r = 0; r < 16; ++r) { p0[r] = 0.f; p1[r] = 0.f; }
;     QK_LD(fa0, fa1, 0); FA_SBAR();
;     QK_LD(fb0, fb1, 1); FA_SBAR(); QK_MM(fa0, fa1, 0); FA_SBAR();
;     QK_LD(fa0, fa1, 2); FA_SBAR(); QK_MM(fb0, fb1, 1); FA_SBAR();
;     QK_LD(fb0, fb1, 3); FA_SBAR(); QK_MM(fa0, fa1, 2); FA_SBAR();
;     if constexpr (NG == 6) {
;         QK_LD(fa0, fa1, 4); FA_SBAR(); QK_MM(fb0, fb1, 3); FA_SBAR();
;         QK_LD(fb0, fb1, 5); FA_SBAR(); QK_MM(fa0, fa1, 4); FA_SBAR();
;         QK_MM(fb0, fb1, 5);
;     } else QK_MM(fb0, fb1, 3);
;     ...
; }
.LBB0_4934:
	s_and_b32 s8, s24, 1
	v_mov_b32_e32 v2, s8
	s_cmp_gt_i32 s22, s17
	s_cbranch_scc1 .Ldsa_skipq
	v_lshlrev_b32_e32 v2, 14, v2
	v_add_u32_e32 v6, v180, v2
	v_add_u32_e32 v196, v6, v181
	v_add_u32_e32 v197, v6, v182
	v_add_u32_e32 v208, v6, v183
	v_add_u32_e32 v209, v6, v184
	ds_read_b128 v[6:9], v196 offset:32768
	ds_read_b128 v[10:13], v196 offset:40960
	ds_read_b128 v[14:17], v197 offset:32768
	ds_read_b128 v[188:191], v197 offset:40960
	ds_read_b128 v[192:195], v208 offset:32768
	ds_read_b128 v[204:207], v208 offset:40960
	ds_read_b128 v[220:223], v209 offset:32768
	ds_read_b128 v[224:227], v209 offset:40960
	s_and_b64 vcc, exec, s[6:7]
	s_cbranch_vccz .Ldsa_q_nold
	v_add_u32_e32 v98, s22, v162
	s_waitcnt vmcnt(0)
	v_add_u32_e32 v100, 64, v98
	v_ashrrev_i32_e32 v101, 31, v100
	v_add_u32_e32 v104, 0x60, v98
	v_lshlrev_b64 v[100:101], 8, v[100:101]
	v_ashrrev_i32_e32 v105, 31, v104
	v_lshl_add_u64 v[102:103], v[166:167], 0, v[100:101]
	v_lshlrev_b64 v[104:105], 8, v[104:105]
	v_lshl_add_u64 v[100:101], v[168:169], 0, v[100:101]
	v_lshl_add_u64 v[106:107], v[166:167], 0, v[104:105]
	global_load_dwordx4 v[114:117], v[102:103], off
	global_load_dwordx4 v[118:121], v[106:107], off
	v_lshl_add_u64 v[102:103], v[168:169], 0, v[104:105]
	global_load_dwordx4 v[122:125], v[100:101], off
	global_load_dwordx4 v[126:129], v[102:103], off
	global_load_dwordx2 v[4:5], v[170:171], off
.Ldsa_q_nold:
	s_waitcnt lgkmcnt(7)
	v_mfma_f32_32x32x16_f16 v[82:97], v[6:9], v[130:133], 0
	s_waitcnt lgkmcnt(6)
	v_mfma_f32_32x32x16_f16 v[98:113], v[10:13], v[130:133], 0
	s_waitcnt lgkmcnt(5)
	v_mfma_f32_32x32x16_f16 v[82:97], v[14:17], v[134:137], v[82:97]
	s_waitcnt lgkmcnt(4)
	v_mfma_f32_32x32x16_f16 v[98:113], v[188:191], v[134:137], v[98:113]
	ds_read_b128 v[6:9], v196 offset:32896
	ds_read_b128 v[10:13], v196 offset:41088
	ds_read_b128 v[14:17], v197 offset:32896
	ds_read_b128 v[188:191], v197 offset:41088
	s_waitcnt lgkmcnt(7)
	v_mfma_f32_32x32x16_f16 v[82:97], v[192:195], v[138:141], v[82:97]
	s_waitcnt lgkmcnt(6)
	v_mfma_f32_32x32x16_f16 v[98:113], v[204:207], v[138:141], v[98:113]
	s_waitcnt lgkmcnt(5)
	v_mfma_f32_32x32x16_f16 v[82:97], v[220:223], v[142:145], v[82:97]
	s_waitcnt lgkmcnt(4)
	v_mfma_f32_32x32x16_f16 v[98:113], v[224:227], v[142:145], v[98:113]
	ds_read_b128 v[192:195], v208 offset:32896
	ds_read_b128 v[204:207], v208 offset:41088
	ds_read_b128 v[220:223], v209 offset:32896
	ds_read_b128 v[224:227], v209 offset:41088
	s_waitcnt lgkmcnt(7)
	v_mfma_f32_32x32x16_f16 v[82:97], v[6:9], v[146:149], v[82:97]
	s_waitcnt lgkmcnt(6)
	v_mfma_f32_32x32x16_f16 v[98:113], v[10:13], v[146:149], v[98:113]
	s_waitcnt lgkmcnt(5)
	v_mfma_f32_32x32x16_f16 v[82:97], v[14:17], v[150:153], v[82:97]
	s_waitcnt lgkmcnt(4)
	v_mfma_f32_32x32x16_f16 v[98:113], v[188:191], v[150:153], v[98:113]
	s_waitcnt lgkmcnt(3)
	v_mfma_f32_32x32x16_f16 v[82:97], v[192:195], v[154:157], v[82:97]
	v_lshrrev_b32_e32 v189, v174, v164
	v_lshrrev_b32_e32 v190, v174, v165
	v_bfe_i32 v6, v189, 0, 1
	v_bfe_i32 v7, v190, 0, 1
	v_bfe_i32 v8, v190, 1, 1
	v_bfe_i32 v9, v190, 2, 1
	v_bfe_i32 v10, v190, 3, 1
	s_waitcnt lgkmcnt(2)
	v_mfma_f32_32x32x16_f16 v[98:113], v[204:207], v[154:157], v[98:113]
	v_bfe_i32 v11, v190, 8, 1
	v_bfe_i32 v12, v190, 9, 1
	v_bfe_i32 v13, v190, 10, 1
	v_bfe_i32 v14, v190, 11, 1
	v_bfe_i32 v15, v190, 16, 1
	v_bfe_i32 v16, v190, 17, 1
	v_bfe_i32 v17, v190, 18, 1
	s_waitcnt lgkmcnt(1)
	v_mfma_f32_32x32x16_f16 v[82:97], v[220:223], v[158:161], v[82:97]
	s_waitcnt lgkmcnt(0)
	v_mfma_f32_32x32x16_f16 v[98:113], v[224:227], v[158:161], v[98:113]
	s_nop 9
	v_bitop3_b32 v188, v82, s36, v6 bitop3:0xe4
	v_bfe_i32 v82, v190, 19, 1
	v_bitop3_b32 v6, v98, s36, v7 bitop3:0xe4
	v_bfe_i32 v7, v189, 1, 1
	v_bitop3_b32 v98, v83, s36, v7 bitop3:0xe4
	v_bitop3_b32 v7, v99, s36, v8 bitop3:0xe4
	v_bfe_i32 v8, v189, 2, 1
	v_bitop3_b32 v99, v84, s36, v8 bitop3:0xe4
	v_bitop3_b32 v8, v100, s36, v9 bitop3:0xe4
	v_bfe_i32 v9, v189, 3, 1
	v_bitop3_b32 v100, v85, s36, v9 bitop3:0xe4
	v_bitop3_b32 v9, v101, s36, v10 bitop3:0xe4
	v_bfe_i32 v10, v189, 8, 1
	v_bitop3_b32 v101, v86, s36, v10 bitop3:0xe4
	v_bitop3_b32 v10, v102, s36, v11 bitop3:0xe4
	v_bfe_i32 v11, v189, 9, 1
	v_bitop3_b32 v87, v87, s36, v11 bitop3:0xe4
	v_bitop3_b32 v11, v103, s36, v12 bitop3:0xe4
	v_bfe_i32 v12, v189, 10, 1
	v_bitop3_b32 v88, v88, s36, v12 bitop3:0xe4
	v_bitop3_b32 v12, v104, s36, v13 bitop3:0xe4
	v_bfe_i32 v13, v189, 11, 1
	v_bitop3_b32 v89, v89, s36, v13 bitop3:0xe4
	v_bitop3_b32 v13, v105, s36, v14 bitop3:0xe4
	v_bfe_i32 v14, v189, 16, 1
	v_bitop3_b32 v90, v90, s36, v14 bitop3:0xe4
	v_bitop3_b32 v14, v106, s36, v15 bitop3:0xe4
	v_bfe_i32 v15, v189, 17, 1
	v_bitop3_b32 v91, v91, s36, v15 bitop3:0xe4
	v_bitop3_b32 v15, v107, s36, v16 bitop3:0xe4
	v_bfe_i32 v16, v189, 18, 1
	v_bitop3_b32 v92, v92, s36, v16 bitop3:0xe4
	v_bitop3_b32 v16, v108, s36, v17 bitop3:0xe4
	v_bfe_i32 v17, v189, 19, 1
	v_bitop3_b32 v93, v93, s36, v17 bitop3:0xe4
	v_bitop3_b32 v17, v109, s36, v82 bitop3:0xe4
	v_bfe_i32 v82, v189, 24, 1
	v_bfe_i32 v83, v190, 24, 1
	v_bitop3_b32 v94, v94, s36, v82 bitop3:0xe4
	v_bitop3_b32 v82, v110, s36, v83 bitop3:0xe4
	v_bfe_i32 v83, v189, 25, 1
	v_bfe_i32 v84, v190, 25, 1
	v_bitop3_b32 v95, v95, s36, v83 bitop3:0xe4
	v_bitop3_b32 v83, v111, s36, v84 bitop3:0xe4
	v_bfe_i32 v84, v189, 26, 1
	v_bfe_i32 v85, v190, 26, 1
	v_bitop3_b32 v96, v96, s36, v84 bitop3:0xe4
	v_bitop3_b32 v84, v112, s36, v85 bitop3:0xe4
	v_bfe_i32 v85, v189, 27, 1
	v_bfe_i32 v86, v190, 27, 1
	v_bitop3_b32 v97, v97, s36, v85 bitop3:0xe4
	v_bitop3_b32 v85, v113, s36, v86 bitop3:0xe4
	v_max_f32_e32 v86, v98, v98
	v_max_f32_e32 v102, v188, v188
	v_max_f32_e32 v86, v102, v86
	v_max3_f32 v86, v86, v99, v100
	v_max3_f32 v86, v86, v101, v87
	v_max3_f32 v86, v86, v88, v89
	v_max3_f32 v86, v86, v90, v91
	v_max3_f32 v86, v86, v92, v93
	v_max3_f32 v86, v86, v94, v95
	v_max3_f32 v86, v86, v96, v97
	v_max3_f32 v86, v86, v6, v7
	v_max3_f32 v86, v86, v8, v9
	v_max3_f32 v86, v86, v10, v11
	v_max3_f32 v86, v86, v12, v13
	v_max3_f32 v86, v86, v14, v15
	v_max3_f32 v86, v86, v16, v17
	v_max3_f32 v86, v86, v82, v83
	v_max3_f32 v86, v86, v84, v85
	v_mov_b32_e32 v102, v86
	s_nop 1
	v_permlane32_swap_b32_e32 v86, v102
	v_max_f32_e32 v102, v102, v102
	v_max_f32_e32 v86, v86, v86
	v_max_f32_e32 v86, v86, v102
	v_sub_f32_e32 v102, v86, v186
	v_mul_f32_e32 v103, 0x3db504f3, v102
	v_max_f32_e32 v102, v186, v186
	v_max_f32_e32 v102, v102, v86
	v_sub_f32_e32 v86, v186, v102
	v_mul_f32_e32 v86, 0x3e0293ee, v86
	v_exp_f32_e32 v86, v86
	v_cmp_ge_f32_e32 vcc, s87, v103
	s_cmp_eq_u64 vcc, exec
	s_cselect_b64 s[38:39], -1, 0
	v_cndmask_b32_e64 v86, v86, 1.0, s[38:39]
	v_cmp_gt_f32_e32 vcc, 1.0, v86
	s_cbranch_vccz .LBB0_4939
	s_and_saveexec_b64 s[8:9], s[0:1]
	ds_write_b32 v179, v86 offset:128
	s_or_b64 exec, exec, s[8:9]
	s_waitcnt lgkmcnt(0)
	ds_read_b128 v[104:107], v1 offset:224
	ds_read_b128 v[108:111], v1 offset:192
	ds_read_b128 v[190:193], v1 offset:160
	ds_read_b128 v[194:197], v1 offset:128
	s_waitcnt lgkmcnt(3)
	v_pk_mul_f32 v[80:81], v[80:81], v[106:107]
	s_waitcnt lgkmcnt(2)
	v_pk_mul_f32 v[76:77], v[76:77], v[110:111]
	s_waitcnt lgkmcnt(1)
	v_pk_mul_f32 v[72:73], v[72:73], v[192:193]
	s_waitcnt lgkmcnt(0)
	v_pk_mul_f32 v[68:69], v[68:69], v[196:197]
	v_pk_mul_f32 v[78:79], v[78:79], v[104:105]
	v_pk_mul_f32 v[74:75], v[74:75], v[108:109]
	v_pk_mul_f32 v[70:71], v[70:71], v[190:191]
	v_pk_mul_f32 v[66:67], v[66:67], v[194:195]
	v_pk_mul_f32 v[64:65], v[64:65], v[106:107]
	v_pk_mul_f32 v[60:61], v[60:61], v[110:111]
	v_pk_mul_f32 v[56:57], v[56:57], v[192:193]
	v_pk_mul_f32 v[52:53], v[52:53], v[196:197]
	v_pk_mul_f32 v[62:63], v[62:63], v[104:105]
	v_pk_mul_f32 v[58:59], v[58:59], v[108:109]
	v_pk_mul_f32 v[54:55], v[54:55], v[190:191]
	v_pk_mul_f32 v[50:51], v[50:51], v[194:195]
	v_pk_mul_f32 v[48:49], v[48:49], v[106:107]
	v_pk_mul_f32 v[44:45], v[44:45], v[110:111]
	v_pk_mul_f32 v[40:41], v[40:41], v[192:193]
	v_pk_mul_f32 v[36:37], v[36:37], v[196:197]
	v_pk_mul_f32 v[46:47], v[46:47], v[104:105]
	v_pk_mul_f32 v[42:43], v[42:43], v[108:109]
	v_pk_mul_f32 v[38:39], v[38:39], v[190:191]
	v_pk_mul_f32 v[34:35], v[34:35], v[194:195]
	v_pk_mul_f32 v[32:33], v[32:33], v[106:107]
	v_pk_mul_f32 v[28:29], v[28:29], v[110:111]
	v_pk_mul_f32 v[24:25], v[24:25], v[192:193]
	v_pk_mul_f32 v[20:21], v[20:21], v[196:197]
	v_pk_mul_f32 v[30:31], v[30:31], v[104:105]
	v_pk_mul_f32 v[26:27], v[26:27], v[108:109]
	v_pk_mul_f32 v[22:23], v[22:23], v[190:191]
	v_pk_mul_f32 v[18:19], v[18:19], v[194:195]

; template <int KIND>
; __device__ __forceinline__ void run_unit(LAS char* lds, const UnitArgs& U, int tid_in) {
;     ...
;     for (int t = 0; t < NT; ++t) {
;         if (t + 1 < NT) FA_LOADT(U.j_lo + t + 1);
.Ldsa_skipq:
	s_and_b64 vcc, exec, s[6:7]
	s_cbranch_vccz .LBB0_4940
	v_add_u32_e32 v2, s22, v162
	s_waitcnt vmcnt(0)
	v_add_u32_e32 v4, 64, v2
	v_ashrrev_i32_e32 v5, 31, v4
	v_add_u32_e32 v8, 0x60, v2
	v_lshlrev_b64 v[4:5], 8, v[4:5]
	v_ashrrev_i32_e32 v9, 31, v8
	v_lshl_add_u64 v[6:7], v[166:167], 0, v[4:5]
	v_lshlrev_b64 v[8:9], 8, v[8:9]
	v_lshl_add_u64 v[4:5], v[168:169], 0, v[4:5]
	v_lshl_add_u64 v[10:11], v[166:167], 0, v[8:9]
	global_load_dwordx4 v[114:117], v[6:7], off
	global_load_dwordx4 v[118:121], v[10:11], off
	v_lshl_add_u64 v[6:7], v[168:169], 0, v[8:9]
	global_load_dwordx4 v[122:125], v[4:5], off
	global_load_dwordx4 v[126:129], v[6:7], off
	s_nop 0
	global_load_dwordx2 v[4:5], v[170:171], off
	s_branch .LBB0_4940
